# v61 + prep x-pass row sums: 6-hop ds_bpermute wave_sum -> DPP moves + permlane swaps
# baseline (speedup 1.0000x reference)
; __device__ __forceinline__ unsigned pk_f16(float lo, float hi) { f32x2 v = {lo, hi}; f16x2_t h = __builtin_convertvector(v, f16x2_t); return __builtin_bit_cast(unsigned, h); }
; __device__ __forceinline__ float wave_sum(float v) {
; #pragma unroll
;     for (int o = 1; o < 64; o <<= 1) v += __shfl_xor(v, o);
;     return v;
; }
; __device__ __forceinline__ void phase_prep(const Args& a, LAS unsigned char* lds, int tid, int lane, int wave) {
;     ...
;       for (int blk = gw; blk < MT / 16; blk += NGW) {
;         const int r0 = blk * 16;
; #pragma unroll 2
;         for (int r = 0; r < 16; ++r) {
;             const f32x4* xr = (const f32x4*)(x + (size_t)(r0 + r) * 1024) + lane;
;             f32x4 v[4]; float s_ = 0.f;
; #pragma unroll
;             for (int j = 0; j < 4; ++j) { v[j] = xr[64 * j]; s_ += (v[j][0] * v[j][0] + v[j][1] * v[j][1]) + (v[j][2] * v[j][2] + v[j][3] * v[j][3]); }
;             s_ = wave_sum(s_);
;             if (lane == 0) rowss[r0 + r] = s_;
;             v2u* x8 = (v2u*)((bf16*)(ws + WS_H) + (size_t)(r0 + r) * 1024) + lane;
; #pragma unroll
;             for (int j = 0; j < 4; ++j) { v2u wx; wx.x = pg8::pk_f16(v[j][0], v[j][1]); wx.y = pg8::pk_f16(v[j][2], v[j][3]); x8[64 * j] = wx; }
;         }
.LBB0_45:
	v_lshl_add_u64 v[14:15], v[26:27], 0, s[8:9]
	global_load_dwordx4 v[6:9], v[14:15], off
	global_load_dwordx4 v[2:5], v[14:15], off offset:1024
	global_load_dwordx4 v[10:13], v[14:15], off offset:2048
	s_nop 0
	global_load_dwordx4 v[14:17], v[14:15], off offset:3072
	s_waitcnt vmcnt(3)
	v_mul_f32_e32 v33, v7, v7
	v_mul_f32_e32 v34, v9, v9
	s_waitcnt vmcnt(2)
	v_mul_f32_e32 v35, v3, v3
	v_mul_f32_e32 v36, v5, v5
	s_waitcnt vmcnt(1)
	v_mul_f32_e32 v37, v11, v11
	v_mul_f32_e32 v38, v13, v13
	v_fmac_f32_e32 v33, v6, v6
	v_fmac_f32_e32 v34, v8, v8
	v_fmac_f32_e32 v35, v2, v2
	v_fmac_f32_e32 v36, v4, v4
	s_waitcnt vmcnt(0)
	v_mul_f32_e32 v39, v15, v15
	v_mul_f32_e32 v40, v17, v17
	v_fmac_f32_e32 v37, v10, v10
	v_fmac_f32_e32 v38, v12, v12
	v_add_f32_e32 v33, v33, v34
	v_add_f32_e32 v34, v35, v36
	v_fmac_f32_e32 v39, v14, v14
	v_fmac_f32_e32 v40, v16, v16
	v_add_f32_e32 v35, v37, v38
	v_add_f32_e32 v33, v33, v34
	v_add_f32_e32 v33, v33, v35
	v_add_f32_e32 v34, v39, v40
	v_add_f32_e32 v33, v33, v34
	s_nop 1
	v_mov_b32_dpp v34, v33 quad_perm:[1,0,3,2] row_mask:0xf bank_mask:0xf
	s_waitcnt lgkmcnt(0)
	v_add_f32_e32 v33, v33, v34
	s_nop 1
	v_mov_b32_dpp v34, v33 quad_perm:[2,3,0,1] row_mask:0xf bank_mask:0xf
	s_waitcnt lgkmcnt(0)
	v_add_f32_e32 v33, v33, v34
	s_nop 1
	v_mov_b32_dpp v34, v33 row_half_mirror row_mask:0xf bank_mask:0xf
	s_waitcnt lgkmcnt(0)
	v_add_f32_e32 v33, v33, v34
	s_nop 1
	v_mov_b32_dpp v34, v33 row_mirror row_mask:0xf bank_mask:0xf
	s_waitcnt lgkmcnt(0)
	v_add_f32_e32 v33, v33, v34
	v_mov_b32_e32 v34, v33
	s_nop 1
	v_permlane16_swap_b32_e32 v34, v33
	s_waitcnt lgkmcnt(0)
	v_add_f32_e32 v33, v33, v34
	v_mov_b32_e32 v34, v33
	s_nop 1
	v_permlane32_swap_b32_e32 v34, v33
	s_and_saveexec_b64 s[12:13], s[0:1]
	s_cbranch_execz .LBB0_47
	s_add_u32 s22, s84, s19
	s_waitcnt lgkmcnt(0)
	v_add_f32_e32 v33, v33, v34
	s_addc_u32 s23, s85, s20
	global_store_dword v19, v33, s[22:23]
.LBB0_47:
	s_or_b64 exec, exec, s[12:13]
	s_waitcnt lgkmcnt(0)
	v_lshl_add_u64 v[34:35], s[84:85], 0, v[24:25]
	v_cvt_pk_f16_f32 v6, v6, v7
	v_cvt_pk_f16_f32 v7, v8, v9
	v_add_co_u32_e32 v8, vcc, 0x3000000, v34
	v_cvt_pk_f16_f32 v2, v2, v3
	s_nop 0
	v_addc_co_u32_e32 v9, vcc, 0, v35, vcc
	v_cvt_pk_f16_f32 v3, v4, v5
	global_store_dwordx2 v[8:9], v[2:3], off offset:512
	v_cvt_pk_f16_f32 v2, v10, v11
	v_cvt_pk_f16_f32 v3, v12, v13
	s_ashr_i32 s11, s10, 31
	global_store_dwordx2 v[8:9], v[2:3], off offset:1024
	v_cvt_pk_f16_f32 v2, v14, v15
	v_cvt_pk_f16_f32 v3, v16, v17
	s_lshl_b64 s[12:13], s[10:11], 12
	global_store_dwordx2 v[8:9], v[6:7], off
	global_store_dwordx2 v[8:9], v[2:3], off offset:1536
	v_lshl_add_u64 v[14:15], v[20:21], 0, s[12:13]
	global_load_dwordx4 v[2:5], v[14:15], off
	global_load_dwordx4 v[6:9], v[14:15], off offset:1024
	global_load_dwordx4 v[10:13], v[14:15], off offset:2048
	s_nop 0
	global_load_dwordx4 v[14:17], v[14:15], off offset:3072
	s_waitcnt vmcnt(3)
	v_mul_f32_e32 v33, v3, v3
	v_mul_f32_e32 v34, v5, v5
	s_waitcnt vmcnt(2)
	v_mul_f32_e32 v35, v7, v7
	v_mul_f32_e32 v36, v9, v9
	s_waitcnt vmcnt(1)
	v_mul_f32_e32 v37, v11, v11
	v_mul_f32_e32 v38, v13, v13
	v_fmac_f32_e32 v33, v2, v2
	v_fmac_f32_e32 v34, v4, v4
	v_fmac_f32_e32 v35, v6, v6
	v_fmac_f32_e32 v36, v8, v8
	s_waitcnt vmcnt(0)
	v_mul_f32_e32 v39, v15, v15
	v_mul_f32_e32 v40, v17, v17
	v_fmac_f32_e32 v37, v10, v10
	v_fmac_f32_e32 v38, v12, v12
	v_add_f32_e32 v33, v33, v34
	v_add_f32_e32 v34, v35, v36
	v_fmac_f32_e32 v39, v14, v14
	v_fmac_f32_e32 v40, v16, v16
	v_add_f32_e32 v35, v37, v38
	v_add_f32_e32 v33, v33, v34
	v_add_f32_e32 v33, v33, v35
	v_add_f32_e32 v34, v39, v40
	v_add_f32_e32 v33, v33, v34
	s_nop 1
	v_mov_b32_dpp v34, v33 quad_perm:[1,0,3,2] row_mask:0xf bank_mask:0xf
	s_waitcnt lgkmcnt(0)
	v_add_f32_e32 v33, v33, v34
	s_nop 1
	v_mov_b32_dpp v34, v33 quad_perm:[2,3,0,1] row_mask:0xf bank_mask:0xf
	s_waitcnt lgkmcnt(0)
	v_add_f32_e32 v33, v33, v34
	s_nop 1
	v_mov_b32_dpp v34, v33 row_half_mirror row_mask:0xf bank_mask:0xf
	s_waitcnt lgkmcnt(0)
	v_add_f32_e32 v33, v33, v34
	s_nop 1
	v_mov_b32_dpp v34, v33 row_mirror row_mask:0xf bank_mask:0xf
	s_waitcnt lgkmcnt(0)
	v_add_f32_e32 v33, v33, v34
	v_mov_b32_e32 v34, v33
	s_nop 1
	v_permlane16_swap_b32_e32 v34, v33
	s_waitcnt lgkmcnt(0)
	v_add_f32_e32 v33, v33, v34
	v_mov_b32_e32 v34, v33
	s_nop 1
	v_permlane32_swap_b32_e32 v34, v33
	s_and_saveexec_b64 s[12:13], s[0:1]
	s_cbranch_execz .LBB0_44
	s_lshl_b64 s[22:23], s[10:11], 2
	s_add_u32 s22, s16, s22
	s_waitcnt lgkmcnt(0)
	v_add_f32_e32 v33, v33, v34
	s_addc_u32 s23, s17, s23
	global_store_dword v19, v33, s[22:23]
	s_branch .LBB0_44
